# mix2 sweep preheader fold: the nine state loads of a fold step issued together (second batch into free registers) instead of two dependent batches
# baseline (speedup 1.0000x reference)
; __device__ void phase_mix2(const Params& P, LAS unsigned char* lds, const int G, const int bid) {
;     ...
;             for (int f = 0; f < nfold; ++f) { const int sp = dir ? nseg - 1 - f : f; const int slot = tot_slot(sg0 + sp, hd, dir);
;                 const float mseg = tots[slot * 2], aseg = tots[slot * 2 + 1];
;                 const float mnew = fmaxf(aseg + m, mseg), d0 = __expf(aseg + m - mnew), d1 = __expf(mseg - mnew);
;                 const float* tp = tot + ((size_t)slot * 512 + threadIdx.x) * 36;
; #pragma unroll
;                 for (int i = 0; i < 9; ++i) C[i] = C[i] * d0 + *(const f32x4*)(tp + 4 * i) * d1;
;                 m = mnew; }
.LBB0_77:
	s_lshl_b32 s14, s10, 1
	s_ashr_i32 s15, s14, 31
	s_lshl_b64 s[14:15], s[14:15], 2
	s_add_u32 s14, s28, s14
	s_addc_u32 s15, s96, s15
	s_waitcnt lgkmcnt(0)
	global_load_dwordx2 v[2:3], v1, s[14:15]
	s_ashr_i32 s11, s10, 31
	s_lshl_b64 s[10:11], s[10:11], 9
	v_lshl_add_u64 v[42:43], s[10:11], 0, v[162:163]
	v_mov_b64_e32 v[40:41], s[52:53]
	s_nop 0
	v_mad_u64_u32 v[40:41], s[10:11], v42, s1, v[40:41]
	v_mad_i32_i24 v41, v43, s1, v41
	global_load_dwordx4 v[42:45], v[40:41], off offset:48
	global_load_dwordx4 v[46:49], v[40:41], off offset:32
	global_load_dwordx4 v[50:53], v[40:41], off offset:16
	global_load_dwordx4 v[54:57], v[40:41], off
	global_load_dwordx4 v[58:61], v[40:41], off offset:112
	global_load_dwordx4 v[62:65], v[40:41], off offset:96
	global_load_dwordx4 v[66:69], v[40:41], off offset:80
	global_load_dwordx4 v[70:73], v[40:41], off offset:64
	global_load_dwordx4 v[74:77], v[40:41], off offset:128
	s_add_i32 s18, s18, 1
	s_add_i32 s19, s19, -1
	s_cmp_eq_u32 s17, s18
	s_waitcnt vmcnt(9)
	v_add_f32_e32 v0, v160, v3
	v_max_f32_e32 v3, v2, v2
	v_max_f32_e32 v160, v0, v3
	v_sub_f32_e32 v2, v2, v160
	v_sub_f32_e32 v0, v0, v160
	v_mul_f32_e32 v2, 0x3fb8aa3b, v2
	v_mul_f32_e32 v0, 0x3fb8aa3b, v0
	v_exp_f32_e32 v2, v2
	v_exp_f32_e32 v0, v0
	s_waitcnt vmcnt(5)
	v_pk_mul_f32 v[56:57], v[56:57], v[2:3] op_sel_hi:[1,0]
	v_pk_mul_f32 v[54:55], v[54:55], v[2:3] op_sel_hi:[1,0]
	v_pk_mul_f32 v[52:53], v[52:53], v[2:3] op_sel_hi:[1,0]
	v_pk_mul_f32 v[50:51], v[50:51], v[2:3] op_sel_hi:[1,0]
	v_pk_mul_f32 v[48:49], v[48:49], v[2:3] op_sel_hi:[1,0]
	v_pk_mul_f32 v[46:47], v[46:47], v[2:3] op_sel_hi:[1,0]
	v_pk_mul_f32 v[44:45], v[44:45], v[2:3] op_sel_hi:[1,0]
	v_pk_mul_f32 v[42:43], v[42:43], v[2:3] op_sel_hi:[1,0]
	v_pk_fma_f32 v[34:35], v[34:35], v[0:1], v[56:57] op_sel_hi:[1,0,1]
	v_pk_fma_f32 v[32:33], v[32:33], v[0:1], v[54:55] op_sel_hi:[1,0,1]
	v_pk_fma_f32 v[30:31], v[30:31], v[0:1], v[52:53] op_sel_hi:[1,0,1]
	v_pk_fma_f32 v[28:29], v[28:29], v[0:1], v[50:51] op_sel_hi:[1,0,1]
	v_pk_fma_f32 v[26:27], v[26:27], v[0:1], v[48:49] op_sel_hi:[1,0,1]
	v_pk_fma_f32 v[24:25], v[24:25], v[0:1], v[46:47] op_sel_hi:[1,0,1]
	v_pk_fma_f32 v[22:23], v[22:23], v[0:1], v[44:45] op_sel_hi:[1,0,1]
	v_pk_fma_f32 v[20:21], v[20:21], v[0:1], v[42:43] op_sel_hi:[1,0,1]
	s_waitcnt vmcnt(4)
	v_pk_mul_f32 v[58:59], v[2:3], v[58:59] op_sel_hi:[0,1]
	s_nop 0
	v_pk_fma_f32 v[4:5], v[4:5], v[0:1], v[58:59] op_sel_hi:[1,0,1]
	s_waitcnt vmcnt(1)
	v_pk_mul_f32 v[72:73], v[72:73], v[2:3] op_sel_hi:[1,0]
	v_pk_mul_f32 v[70:71], v[70:71], v[2:3] op_sel_hi:[1,0]
	v_pk_mul_f32 v[68:69], v[68:69], v[2:3] op_sel_hi:[1,0]
	v_pk_mul_f32 v[66:67], v[66:67], v[2:3] op_sel_hi:[1,0]
	v_pk_mul_f32 v[64:65], v[2:3], v[64:65] op_sel_hi:[0,1]
	v_pk_mul_f32 v[62:63], v[2:3], v[62:63] op_sel_hi:[0,1]
	v_pk_mul_f32 v[60:61], v[2:3], v[60:61] op_sel_hi:[0,1]
	v_pk_fma_f32 v[18:19], v[18:19], v[0:1], v[72:73] op_sel_hi:[1,0,1]
	v_pk_fma_f32 v[16:17], v[16:17], v[0:1], v[70:71] op_sel_hi:[1,0,1]
	v_pk_fma_f32 v[14:15], v[14:15], v[0:1], v[68:69] op_sel_hi:[1,0,1]
	v_pk_fma_f32 v[12:13], v[12:13], v[0:1], v[66:67] op_sel_hi:[1,0,1]
	v_pk_fma_f32 v[10:11], v[10:11], v[0:1], v[64:65] op_sel_hi:[1,0,1]
	v_pk_fma_f32 v[8:9], v[8:9], v[0:1], v[62:63] op_sel_hi:[1,0,1]
	v_pk_fma_f32 v[6:7], v[6:7], v[0:1], v[60:61] op_sel_hi:[1,0,1]
	s_waitcnt vmcnt(0)
	v_pk_mul_f32 v[76:77], v[2:3], v[76:77] op_sel_hi:[0,1]
	v_pk_mul_f32 v[2:3], v[2:3], v[74:75] op_sel_hi:[0,1]
	v_pk_fma_f32 v[38:39], v[38:39], v[0:1], v[76:77] op_sel_hi:[1,0,1]
	v_pk_fma_f32 v[36:37], v[36:37], v[0:1], v[2:3] op_sel_hi:[1,0,1]
	s_cbranch_scc1 .LBB0_83
